# attention unit prologue: first-row Q loads issued with the K/V tile loads instead of after the staging barrier (one fewer serialized round trip per unit)
# speedup vs baseline: 1.0038x; 1.0032x over previous
.LBB0_121:
	s_lshl_b32 s0, s14, 11
	s_waitcnt vmcnt(0)
	v_add_u32_e32 v0, s0, v79
	v_ashrrev_i32_e32 v1, 31, v0
	v_readlane_b32 s4, v251, 6
	v_lshlrev_b64 v[0:1], 12, v[0:1]
	v_readlane_b32 s5, v251, 7
	s_lshl_b32 s26, s13, 1
	v_readlane_b32 s2, v251, 8
	v_lshl_add_u64 v[0:1], s[4:5], 0, v[0:1]
	v_lshl_add_u64 v[0:1], v[0:1], 0, s[26:27]
	v_readlane_b32 s3, v251, 9
	v_lshl_add_u64 v[70:71], v[0:1], 0, v[152:153]
	v_add_u32_e32 v2, s13, v79
	v_mov_b64_e32 v[0:1], s[2:3]
	v_mad_i64_i32 v[0:1], s[2:3], v2, s23, v[0:1]
	s_ashr_i32 s1, s0, 31
	v_lshl_add_u64 v[0:1], s[0:1], 1, v[0:1]
	v_lshl_add_u64 v[72:73], v[0:1], 0, v[152:153]
	global_load_dwordx4 v[182:185], v[70:71], off offset:2048
	global_load_dwordx4 v[186:189], v[72:73], off
	global_load_dwordx4 v[8:11], v[72:73], off offset:128
	s_mov_b32 s1, 0x40000
	v_add_co_u32_e32 v12, vcc, s1, v70
	s_add_i32 s2, s10, s0
	s_nop 0
	v_addc_co_u32_e32 v13, vcc, 0, v71, vcc
	global_load_dwordx4 v[12:15], v[12:13], off offset:2048
	v_or_b32_e32 v20, s2, v63
	v_ashrrev_i32_e32 v21, 31, v20
	v_add_co_u32_e32 v24, vcc, s25, v70
	v_lshlrev_b64 v[20:21], 12, v[20:21]
	s_nop 0
	v_addc_co_u32_e32 v25, vcc, 0, v71, vcc
	v_lshl_add_u64 v[20:21], s[4:5], 0, v[20:21]
	v_add_co_u32_e32 v26, vcc, s31, v70
	v_add_u32_e32 v96, 0x18800, v235
	v_lshl_add_u64 v[20:21], v[20:21], 0, s[26:27]
	v_addc_co_u32_e32 v27, vcc, 0, v71, vcc
	v_add_u32_e32 v93, 0x12000, v92
	v_add_u32_e32 v94, 0x14000, v235
	v_add_u32_e32 v95, 0x16800, v92
	global_load_dwordx4 v[16:19], v[72:73], off offset:256
	v_lshl_add_u64 v[32:33], v[56:57], 1, v[20:21]
	global_load_dwordx4 v[20:23], v[72:73], off offset:384
	global_load_dwordx4 v[28:31], v[24:25], off offset:2048
	s_nop 0
	global_load_dwordx4 v[24:27], v[26:27], off offset:2048
	global_load_dwordx4 v[0:3], v[32:33], off
	global_load_dwordx4 v[4:7], v[32:33], off offset:64
	v_mov_b32_e32 v100, 0
	s_mov_b32 s1, 0
	s_or_b32 s0, s0, s8
	v_lshl_add_u64 v[74:75], v[58:59], 0, s[26:27]
	v_lshl_add_u64 v[76:77], v[60:61], 0, s[26:27]
	v_mov_b32_e32 v101, 0xf149f2ca
	s_mov_b32 s15, 4
	s_mov_b32 s5, 8
	s_mov_b32 s3, -3
	v_mov_b32_e32 v97, 0
	v_mov_b32_e32 v98, 8
	v_mov_b32_e32 v99, 0
	s_mov_b32 s14, 0
	s_mov_b32 s13, s9
	s_mov_b32 s4, 0
	s_mov_b32 s16, 4
	v_mov_b32_e32 v34, v100
	v_mov_b32_e32 v35, v100
	v_mov_b32_e32 v36, v100
	v_mov_b32_e32 v37, v100
	v_mov_b32_e32 v38, v100
	v_mov_b32_e32 v39, v100
	v_mov_b32_e32 v40, v100
	v_mov_b32_e32 v41, v100
	v_mov_b32_e32 v42, v100
	v_mov_b32_e32 v43, v100
	v_mov_b32_e32 v44, v100
	v_mov_b32_e32 v45, v100
	v_mov_b32_e32 v46, v100
	v_mov_b32_e32 v47, v100
	s_waitcnt vmcnt(7)
	ds_write_b128 v96, v[8:11]
	ds_write_b128 v94, v[186:189]
	ds_write_b128 v93, v[182:185]
	s_waitcnt vmcnt(6)
	ds_write_b128 v95, v[12:15]
	s_waitcnt lgkmcnt(0)
	s_barrier
	v_mov_b32_e32 v8, v153
	v_mov_b32_e32 v9, v153
	v_mov_b32_e32 v10, v153
	v_mov_b32_e32 v11, v153
	v_mov_b32_e32 v12, v153
	v_mov_b32_e32 v13, v153
	v_mov_b32_e32 v14, v153
	v_mov_b32_e32 v15, v153
	v_mov_b32_e32 v32, 0
	v_mov_b32_e32 v33, v100
	v_add_u32_e32 v226, 0x1b000, v92
	v_add_u32_e32 v227, 0x1d000, v235
	v_mov_b32_e32 v144, 0x3f803f80
	v_mov_b32_e32 v145, v144
	v_mov_b32_e32 v146, v144
	v_mov_b32_e32 v147, v144
	v_sub_u32_e32 v102, v97, v99
	v_add_u32_e32 v102, s14, v102
	v_cmp_gt_u32_e32 vcc, 8, v102
	s_cbranch_vccz .Lpf_skip_init
	v_mad_u32_u24 v103, v102, s34, v67
	v_subrev_u32_e32 v120, s13, v99
	ds_read_b128 v[166:169], v103 offset:3072
	ds_read_b128 v[174:177], v103 offset:5120
	ds_read_b128 v[170:173], v103 offset:4096
	ds_read_b128 v[178:181], v103 offset:6144
	v_add3_u32 v120, v120, v102, 7
	ds_read_b128 v[182:185], v81 offset:0
	ds_read_b128 v[190:193], v81 offset:256
	ds_read_b128 v[186:189], v82 offset:0
	ds_read_b128 v[194:197], v82 offset:256
	v_lshl_add_u32 v120, v120, 8, v162
	ds_read_b128 v[112:115], v120
	ds_read_b128 v[116:119], v120 offset:16
	s_waitcnt lgkmcnt(10)
